# loop-edge edits in attn-B tile loop: diagonal block out of line, simplified post-L barrier select, rotated back edge (on top of no-drain)
# baseline (speedup 1.0000x reference)
.LBB0_698:
	s_add_i32 s12, s29, 0xffff8000
	s_add_i32 s16, s29, 0x4000
	s_and_b32 s13, s16, 0xc000
	s_and_b32 s12, s12, 0xc000
	v_add_u32_e32 v2, s12, v172
	ds_read_b128 v[186:189], v2 offset:0
	ds_read_b128 v[190:193], v2 offset:0x2000
	v_add_u32_e32 v2, s12, v173
	ds_read_b128 v[194:197], v2 offset:0
	ds_read_b128 v[198:201], v2 offset:0x2000
	v_add_u32_e32 v2, s12, v184
	ds_read_b128 v[202:205], v2 offset:0
	ds_read_b128 v[206:209], v2 offset:0x2000
	v_add_u32_e32 v2, s12, v185
	ds_read_b128 v[210:213], v2 offset:0
	ds_read_b128 v[214:217], v2 offset:0x2000
	v_add_u32_e32 v149, s13, v171
	ds_read_b64_tr_b16 v[218:219], v149 offset:0
	ds_read_b64_tr_b16 v[220:221], v149 offset:0x800
	ds_read_b64_tr_b16 v[222:223], v149 offset:0x1000
	ds_read_b64_tr_b16 v[224:225], v149 offset:0x1800
	ds_read_b64_tr_b16 v[226:227], v149 offset:0x2000
	ds_read_b64_tr_b16 v[228:229], v149 offset:0x2800
	ds_read_b64_tr_b16 v[242:243], v149 offset:0x3000
	ds_read_b64_tr_b16 v[244:245], v149 offset:0x3800
	s_cmp_gt_i32 s27, s19
	s_cselect_b64 vcc, -1, 0
	s_and_b64 s[12:13], vcc, exec
	s_cselect_b32 s12, 0x8000, 0
	v_xor_b32_e32 v2, s12, v164
	v_mov_b32_e32 v4, v3
	v_mov_b32_e32 v5, v3
	s_waitcnt lgkmcnt(8)
	s_nop 1
	v_mfma_f32_32x32x16_bf16 v[70:85], v[118:121], v[2:5], 0
	v_mfma_f32_32x32x16_bf16 v[86:101], v[186:189], v[102:105], v[70:85]
	v_mfma_f32_32x32x16_bf16 v[70:85], v[190:193], v[102:105], v[70:85]
	v_mfma_f32_32x32x16_bf16 v[86:101], v[194:197], v[106:109], v[86:101]
	v_mfma_f32_32x32x16_bf16 v[70:85], v[198:201], v[106:109], v[70:85]
	v_mfma_f32_32x32x16_bf16 v[86:101], v[202:205], v[110:113], v[86:101]
	v_mfma_f32_32x32x16_bf16 v[70:85], v[206:209], v[110:113], v[70:85]
	v_mfma_f32_32x32x16_bf16 v[86:101], v[210:213], v[114:117], v[86:101]
	v_mfma_f32_32x32x16_bf16 v[70:85], v[214:217], v[114:117], v[70:85]
	ds_read_b64_tr_b16 v[186:187], v149 offset:0x200
	ds_read_b64_tr_b16 v[188:189], v149 offset:0xa00
	ds_read_b64_tr_b16 v[190:191], v149 offset:0x1200
	ds_read_b64_tr_b16 v[192:193], v149 offset:0x1a00
	ds_read_b64_tr_b16 v[194:195], v149 offset:0x2200
	ds_read_b64_tr_b16 v[196:197], v149 offset:0x2a00
	ds_read_b64_tr_b16 v[198:199], v149 offset:0x3200
	ds_read_b64_tr_b16 v[200:201], v149 offset:0x3a00
	s_waitcnt lgkmcnt(8)
	v_mfma_f32_32x32x16_bf16 v[54:69], v[134:137], v[218:221], v[54:69]
	v_mfma_f32_32x32x16_bf16 v[54:69], v[130:133], v[222:225], v[54:69]
	v_mfma_f32_32x32x16_bf16 v[54:69], v[126:129], v[226:229], v[54:69]
	v_mfma_f32_32x32x16_bf16 v[54:69], v[122:125], v[242:245], v[54:69]
	ds_read_b64_tr_b16 v[202:203], v149 offset:0x400
	ds_read_b64_tr_b16 v[204:205], v149 offset:0xc00
	ds_read_b64_tr_b16 v[206:207], v149 offset:0x1400
	ds_read_b64_tr_b16 v[208:209], v149 offset:0x1c00
	ds_read_b64_tr_b16 v[210:211], v149 offset:0x2400
	ds_read_b64_tr_b16 v[212:213], v149 offset:0x2c00
	ds_read_b64_tr_b16 v[214:215], v149 offset:0x3400
	ds_read_b64_tr_b16 v[216:217], v149 offset:0x3c00
	s_waitcnt lgkmcnt(8)
	v_mfma_f32_32x32x16_bf16 v[38:53], v[134:137], v[186:189], v[38:53]
	v_mfma_f32_32x32x16_bf16 v[38:53], v[130:133], v[190:193], v[38:53]
	v_mfma_f32_32x32x16_bf16 v[38:53], v[126:129], v[194:197], v[38:53]
	v_mfma_f32_32x32x16_bf16 v[38:53], v[122:125], v[198:201], v[38:53]
	ds_read_b64_tr_b16 v[186:187], v149 offset:0x600
	ds_read_b64_tr_b16 v[188:189], v149 offset:0xe00
	ds_read_b64_tr_b16 v[190:191], v149 offset:0x1600
	ds_read_b64_tr_b16 v[192:193], v149 offset:0x1e00
	ds_read_b64_tr_b16 v[194:195], v149 offset:0x2600
	ds_read_b64_tr_b16 v[196:197], v149 offset:0x2e00
	ds_read_b64_tr_b16 v[198:199], v149 offset:0x3600
	ds_read_b64_tr_b16 v[200:201], v149 offset:0x3e00
	s_waitcnt lgkmcnt(8)
	v_mfma_f32_32x32x16_bf16 v[22:37], v[134:137], v[202:205], v[22:37]
	v_mfma_f32_32x32x16_bf16 v[22:37], v[130:133], v[206:209], v[22:37]
	v_mfma_f32_32x32x16_bf16 v[22:37], v[126:129], v[210:213], v[22:37]
	v_mfma_f32_32x32x16_bf16 v[22:37], v[122:125], v[214:217], v[22:37]
	s_waitcnt lgkmcnt(0)
	v_mfma_f32_32x32x16_bf16 v[6:21], v[134:137], v[186:189], v[6:21]
	v_mfma_f32_32x32x16_bf16 v[6:21], v[130:133], v[190:193], v[6:21]
	v_mfma_f32_32x32x16_bf16 v[6:21], v[126:129], v[194:197], v[6:21]
	v_mfma_f32_32x32x16_bf16 v[6:21], v[122:125], v[198:201], v[6:21]
	s_waitcnt lgkmcnt(0)
	s_barrier
	s_add_i32 s12, s28, 0xffffff80
	v_cvt_f32_u32_e32 v2, s12
	s_cmp_lg_u32 s19, s27
	v_sub_f32_e32 v4, v163, v2
	s_cbranch_scc0 .Lb_diag

.LBB0_704:
	s_add_i32 s12, s10, s27
	s_add_i32 s17, s12, 2
	s_cmp_gt_i32 s17, s11
	s_cbranch_scc1 .Lb_nodma
	s_add_i32 vcc_lo, s18, s28
	s_ashr_i32 vcc_hi, vcc_lo, 31
	s_lshl_b64 vcc, vcc, 8
	s_add_u32 s94, s89, vcc_lo
	s_addc_u32 s95, s50, vcc_hi
	s_add_u32 vcc_lo, s78, vcc_lo
	s_addc_u32 vcc_hi, s88, vcc_hi
	s_add_i32 s17, s23, s29
	s_and_b32 s17, s17, 0xc000
	s_add_i32 s29, s17, s91
	s_add_i32 s17, s17, s51
	v_lshl_add_u64 v[70:71], s[94:95], 0, v[140:141]
	s_mov_b32 m0, s29
	s_nop 0
	global_load_lds_dwordx4 v[70:71], off
	v_lshl_add_u64 v[70:71], vcc, 0, v[142:143]
	s_mov_b32 m0, s17
	s_nop 0
	global_load_lds_dwordx4 v[70:71], off
	v_lshl_add_u64 v[70:71], s[94:95], 0, v[144:145]
	s_add_i32 m0, s29, 0x400
	s_nop 0
	global_load_lds_dwordx4 v[70:71], off
	v_lshl_add_u64 v[70:71], vcc, 0, v[146:147]
	s_add_i32 m0, s17, 0x400
	s_nop 0
	global_load_lds_dwordx4 v[70:71], off
	s_waitcnt vmcnt(4) lgkmcnt(0)
	s_barrier
.LBB0_710:
	v_add_f32_e32 v4, v4, v5
	v_fmac_f32_e32 v4, v170, v2
	s_add_i32 s27, s27, 1
	s_add_i32 s12, s22, s27
	s_add_i32 s28, s28, 64
	v_mov_b32_e32 v170, v4
	s_cmp_eq_u32 s12, 1
	s_cselect_b32 s29, s29, s16
	s_cbranch_scc0 .LBB0_698
	s_branch .LBB0_714
.Lb_nodma:
	s_waitcnt vmcnt(0) lgkmcnt(0)
	s_barrier
	s_branch .LBB0_710
.Lb_diag:
	v_sub_f32_e32 v2, v4, v165
	v_sub_f32_e32 v5, 0x42000000, v2
	v_max_f32_e32 v124, 0, v5
	v_sub_f32_e32 v5, 1.0, v2
	v_max_f32_e32 v123, 0, v5
	v_sub_f32_e32 v5, 0x42040000, v2
	v_max_f32_e32 v125, 0, v5
	v_sub_f32_e32 v5, 2.0, v2
	v_max_f32_e32 v126, 0, v5
	v_sub_f32_e32 v5, 0x42080000, v2
	v_max_f32_e32 v128, 0, v5
	v_sub_f32_e32 v5, 0x40400000, v2
	v_max_f32_e32 v127, 0, v5
	v_sub_f32_e32 v5, 0x420c0000, v2
	v_max_f32_e32 v129, 0, v5
	v_sub_f32_e32 v5, 0x41000000, v2
	v_max_f32_e32 v130, 0, v5
	v_sub_f32_e32 v5, 0x42200000, v2
	v_max_f32_e32 v132, 0, v5
	v_sub_f32_e32 v5, 0x41100000, v2
	v_max_f32_e32 v131, 0, v5
	v_sub_f32_e32 v5, 0x42240000, v2
	v_max_f32_e32 v133, 0, v5
	v_sub_f32_e32 v5, 0x41200000, v2
	v_max_f32_e32 v134, 0, v5
	v_sub_f32_e32 v5, 0x42280000, v2
	v_max_f32_e32 v136, 0, v5
	v_sub_f32_e32 v5, 0x41300000, v2
	v_max_f32_e32 v135, 0, v5
	v_sub_f32_e32 v5, 0x422c0000, v2
	v_max_f32_e32 v137, 0, v5
	v_sub_f32_e32 v5, 0x41800000, v2
	v_max_f32_e32 v174, 0, v5
	v_sub_f32_e32 v5, 0x42400000, v2
	v_max_f32_e32 v176, 0, v5
	v_sub_f32_e32 v5, 0x41880000, v2
	v_max_f32_e32 v175, 0, v5
	v_sub_f32_e32 v5, 0x42440000, v2
	v_max_f32_e32 v177, 0, v5
	v_sub_f32_e32 v5, 0x41900000, v2
	v_max_f32_e32 v178, 0, v5
	v_sub_f32_e32 v5, 0x42480000, v2
	v_max_f32_e32 v180, 0, v5
	v_sub_f32_e32 v5, 0x41980000, v2
	v_max_f32_e32 v179, 0, v5
	v_sub_f32_e32 v5, 0x424c0000, v2
	v_max_f32_e32 v181, 0, v5
	v_sub_f32_e32 v5, 0x41c00000, v2
	v_max_f32_e32 v182, 0, v5
	v_sub_f32_e32 v5, 0x42600000, v2
	v_max_f32_e32 v186, 0, v5
	v_sub_f32_e32 v5, 0x41c80000, v2
	v_max_f32_e32 v183, 0, v5
	v_sub_f32_e32 v5, 0x42640000, v2
	v_max_f32_e32 v187, 0, v5
	v_sub_f32_e32 v5, 0x41d00000, v2
	v_max_f32_e32 v188, 0, v5
	v_sub_f32_e32 v5, 0x42680000, v2
	v_max_f32_e64 v122, -v2, 0
	v_max_f32_e32 v190, 0, v5
	v_sub_f32_e32 v5, 0x41d80000, v2
	v_sub_f32_e32 v2, 0x426c0000, v2
	v_max_f32_e32 v189, 0, v5
	v_mov_b32_e32 v149, v148
	v_max_f32_e32 v191, 0, v2
	v_pk_fma_f32 v[100:101], v[188:189], v[148:149], v[100:101]
	v_pk_fma_f32 v[98:99], v[182:183], v[148:149], v[98:99]
	v_pk_fma_f32 v[96:97], v[178:179], v[148:149], v[96:97]
	v_pk_fma_f32 v[94:95], v[174:175], v[148:149], v[94:95]
	v_pk_fma_f32 v[92:93], v[134:135], v[148:149], v[92:93]
	v_pk_fma_f32 v[90:91], v[130:131], v[148:149], v[90:91]
	v_pk_fma_f32 v[88:89], v[126:127], v[148:149], v[88:89]
	v_pk_fma_f32 v[86:87], v[122:123], v[150:151], v[86:87]
	v_pk_fma_f32 v[84:85], v[190:191], v[148:149], v[84:85]
	v_pk_fma_f32 v[82:83], v[186:187], v[148:149], v[82:83]
	v_pk_fma_f32 v[80:81], v[180:181], v[148:149], v[80:81]
	v_pk_fma_f32 v[78:79], v[176:177], v[148:149], v[78:79]
	v_pk_fma_f32 v[76:77], v[136:137], v[148:149], v[76:77]
	v_pk_fma_f32 v[74:75], v[132:133], v[148:149], v[74:75]
	v_pk_fma_f32 v[72:73], v[128:129], v[148:149], v[72:73]
	v_pk_fma_f32 v[70:71], v[124:125], v[150:151], v[70:71]
	s_branch .LBB0_700
